# panel barriers: census result cached for SEAM(6); P7 EpiD: redundant buffer_inv after the 4-WG spin removed (its cross-WG loads are sc1)
# baseline (speedup 1.0000x reference)
; __device__ __forceinline__ unsigned xb_ld(unsigned* p)              { return __hip_atomic_load(p, __ATOMIC_RELAXED, __HIP_MEMORY_SCOPE_AGENT); }
; __device__ __forceinline__ unsigned xb_add(unsigned* p, unsigned v) { return __hip_atomic_fetch_add(p, v, __ATOMIC_RELAXED, __HIP_MEMORY_SCOPE_AGENT); }
; #define XB_SPIN(cond, bar) do { unsigned _sp = 0; while (cond) { __builtin_amdgcn_s_sleep(1); \
;     if ((++_sp & 255u) == 0u) { if (xb_ld(&(bar)[XB_TMO])) break; if (_sp > XB_SPIN_CAP) { atomicAdd(&(bar)[XB_TMO], 1u); break; } } } } while (0)
; #define SEAM(k) do { if (IN(k) && IN((k) + 1)) xcd_barrier(bar); } while (0)
; __device__ __forceinline__ void xcd_barrier(const XcdBarrier& b) {
;     asm volatile("s_waitcnt vmcnt(0)" ::: "memory");
;     __syncthreads();
;     if (threadIdx.x == 0) {
;         unsigned* bar = b.bar;
;         __builtin_amdgcn_s_waitcnt(0);
;         unsigned nloc = b.st[0], nx = b.st[1];
;         if (nloc == 0u) { xcd_barrier_complete(bar, b.x, nloc, nx); b.st[0] = nloc; b.st[1] = nx; }
;         const unsigned old = xb_add(&bar[XB_XSUB(b.x)], 1u);
;         const unsigned gen = old / nloc;
;         if (old + 1u == (gen + 1u) * nloc) {
;             __builtin_amdgcn_fence(__ATOMIC_RELEASE, "agent");
;             asm volatile("s_waitcnt vmcnt(0)" ::: "memory");
;             const unsigned og = xb_add(&bar[XB_TOP], 1u);
;             const unsigned tg = og / nx;
;             if (og + 1u == (tg + 1u) * nx) xb_add(&bar[XB_TOPGEN], 1u);
;             else XB_SPIN(xb_ld(&bar[XB_TOPGEN]) == tg, bar);
;             __builtin_amdgcn_fence(__ATOMIC_ACQUIRE, "agent");
;             xb_add(&bar[XB_XGEN(b.x)], 1u);
;             asm volatile("s_waitcnt vmcnt(0)" ::: "memory");
;         } else {
;             XB_SPIN(xb_ld(&bar[XB_XGEN(b.x)]) == gen, bar);
;             __builtin_amdgcn_fence(__ATOMIC_ACQUIRE, "agent");
;             asm volatile("s_waitcnt vmcnt(0)" ::: "memory");
;         }
;     }
;     __syncthreads();
; }
; __global__ void __launch_bounds__(512, 2) mk_fwd(Args args) {
;     ...
;     SEAM(5);
.LBB0_535:
	s_cmp_gt_i32 s69, 6
	s_cselect_b64 s[4:5], -1, 0
	s_and_b64 s[0:1], s[6:7], s[4:5]
	s_andn2_b64 vcc, exec, s[0:1]
	s_cbranch_vccnz .LBB0_589
	s_waitcnt vmcnt(0)
	s_waitcnt vmcnt(0)
	s_barrier
	s_and_saveexec_b64 s[6:7], s[92:93]
	s_cbranch_execz .LBB0_588
	s_and_b32 s0, s2, 63
	s_lshl_b32 s1, s0, 8
	v_mov_b32_e32 v1, 1
	s_add_u32 s1, s1, 0xc000
	v_mov_b32_e32 v3, s1
	global_load_dword v2, v3, s[66:67] sc1
	s_lshl_b32 s0, s0, 7
	s_add_u32 s0, s0, 0x8000
	v_mov_b32_e32 v0, s0
	s_getreg_b32 s8, hwreg(HW_REG_XCC_ID, 0, 4)
	s_and_b32 s8, s8, 7
	s_mul_i32 s8, s8, 3
	s_waitcnt vmcnt(0)
	v_readfirstlane_b32 s1, v2
	s_lshr_b32 s1, s1, s8
	s_and_b32 s1, s1, 7
	v_writelane_b32 v251, s1, 9
	s_cmp_eq_u32 s1, 4
	s_cbranch_scc1 .Lpb5_fast
	buffer_wbl2 sc1
	s_waitcnt vmcnt(0)

; __device__ __forceinline__ unsigned xb_ld(unsigned* p)              { return __hip_atomic_load(p, __ATOMIC_RELAXED, __HIP_MEMORY_SCOPE_AGENT); }
; __device__ __forceinline__ unsigned xb_add(unsigned* p, unsigned v) { return __hip_atomic_fetch_add(p, v, __ATOMIC_RELAXED, __HIP_MEMORY_SCOPE_AGENT); }
; #define XB_SPIN(cond, bar) do { unsigned _sp = 0; while (cond) { __builtin_amdgcn_s_sleep(1); \
;     if ((++_sp & 255u) == 0u) { if (xb_ld(&(bar)[XB_TMO])) break; if (_sp > XB_SPIN_CAP) { atomicAdd(&(bar)[XB_TMO], 1u); break; } } } } while (0)
; #define SEAM(k) do { if (IN(k) && IN((k) + 1)) xcd_barrier(bar); } while (0)
; __device__ __forceinline__ void xcd_barrier(const XcdBarrier& b) {
;     asm volatile("s_waitcnt vmcnt(0)" ::: "memory");
;     __syncthreads();
;     if (threadIdx.x == 0) {
;         unsigned* bar = b.bar;
;         __builtin_amdgcn_s_waitcnt(0);
;         unsigned nloc = b.st[0], nx = b.st[1];
;         if (nloc == 0u) { xcd_barrier_complete(bar, b.x, nloc, nx); b.st[0] = nloc; b.st[1] = nx; }
;         const unsigned old = xb_add(&bar[XB_XSUB(b.x)], 1u);
;         const unsigned gen = old / nloc;
;         if (old + 1u == (gen + 1u) * nloc) {
;             __builtin_amdgcn_fence(__ATOMIC_RELEASE, "agent");
;             asm volatile("s_waitcnt vmcnt(0)" ::: "memory");
;             const unsigned og = xb_add(&bar[XB_TOP], 1u);
;             const unsigned tg = og / nx;
;             if (og + 1u == (tg + 1u) * nx) xb_add(&bar[XB_TOPGEN], 1u);
;             else XB_SPIN(xb_ld(&bar[XB_TOPGEN]) == tg, bar);
;             __builtin_amdgcn_fence(__ATOMIC_ACQUIRE, "agent");
;             xb_add(&bar[XB_XGEN(b.x)], 1u);
;             asm volatile("s_waitcnt vmcnt(0)" ::: "memory");
;         } else {
;             XB_SPIN(xb_ld(&bar[XB_XGEN(b.x)]) == gen, bar);
;             __builtin_amdgcn_fence(__ATOMIC_ACQUIRE, "agent");
;             asm volatile("s_waitcnt vmcnt(0)" ::: "memory");
;         }
;     }
;     __syncthreads();
; }
; __global__ void __launch_bounds__(512, 2) mk_fwd(Args args) {
;     ...
;     SEAM(6);
.LBB0_696:
	s_cmp_gt_i32 s69, 7
	s_cselect_b64 s[4:5], -1, 0
	s_and_b64 s[0:1], s[8:9], s[4:5]
	s_andn2_b64 vcc, exec, s[0:1]
	s_cbranch_vccnz .LBB0_750
	s_waitcnt vmcnt(0)
	s_waitcnt vmcnt(0)
	s_barrier
	s_and_saveexec_b64 s[6:7], s[92:93]
	s_cbranch_execz .LBB0_749
	s_and_b32 s0, s2, 63
	v_mov_b32_e32 v1, 1
	s_lshl_b32 s0, s0, 7
	s_add_u32 s0, s0, 0xa000
	v_mov_b32_e32 v0, s0
	v_readlane_b32 s1, v251, 9
	s_nop 0
	s_cmp_eq_u32 s1, 4
	s_cbranch_scc1 .Lpb6_fast
	buffer_wbl2 sc1
	s_waitcnt vmcnt(0)

;     __device__ __forceinline__ void fused(f32x4 (&acc)[2][2][4][2], const pg8::Unit& u, int wr, int wc, int fr, int fq, LAS unsigned char* lds, int wid, int lane) const {
;     ...
;         if (tid == 0) {
;             unsigned* c = cnt + 64 * u.pm;
;             (void)__hip_atomic_fetch_add(c, 1u, __ATOMIC_RELAXED, __HIP_MEMORY_SCOPE_AGENT);
;             unsigned sp = 0;
;             while (__hip_atomic_load(c, __ATOMIC_RELAXED, __HIP_MEMORY_SCOPE_AGENT) < 4u) { __builtin_amdgcn_s_sleep(2); if (++sp > (1u << 22)) break; }
;             __builtin_amdgcn_fence(__ATOMIC_ACQUIRE, "agent");
;             asm volatile("s_waitcnt vmcnt(0)" ::: "memory");
;         }
;         __syncthreads();
;         if (tid < 256) {
;             float t = 0.f;
; #pragma unroll
;             for (int pn = 0; pn < 4; ++pn) t += __hip_atomic_load(xb + ((size_t)(u.pm * 4 + pn)) * 256 + tid, __ATOMIC_RELAXED, __HIP_MEMORY_SCOPE_AGENT);
;             Sr[tid] = __builtin_amdgcn_rsqf(t * (1.f / 1024.f) + RMS_EPS);
.LBB0_798:
	global_load_dword v1, v0, s[0:1] sc1
	s_mov_b64 s[10:11], -1
	s_waitcnt vmcnt(0)
	v_cmp_lt_u32_e32 vcc, 3, v1
	s_cbranch_vccnz .LBB0_797
	s_sleep 2
	global_load_dword v1, v0, s[0:1] sc1
	s_waitcnt vmcnt(0)
	v_cmp_gt_u32_e32 vcc, 4, v1
	s_cbranch_vccz .LBB0_797
	s_sleep 2
	global_load_dword v1, v0, s[0:1] sc1
	s_waitcnt vmcnt(0)
	v_cmp_gt_u32_e32 vcc, 4, v1
	s_cbranch_vccz .LBB0_797
	s_sleep 2
	global_load_dword v1, v0, s[0:1] sc1
	s_waitcnt vmcnt(0)
	v_cmp_gt_u32_e32 vcc, 4, v1
	s_cbranch_vccz .LBB0_797
	s_sleep 2
	global_load_dword v1, v0, s[0:1] sc1
	s_waitcnt vmcnt(0)
	v_cmp_gt_u32_e32 vcc, 4, v1
	s_cbranch_vccz .LBB0_797
	s_add_i32 s12, s12, -5
	s_cmp_eq_u32 s12, 0
	s_cselect_b64 s[10:11], -1, 0
	s_sleep 2
	s_branch .LBB0_797
.LBB0_804:
	s_waitcnt vmcnt(0)
.LBB0_805:
	s_or_b64 exec, exec, s[6:7]
	s_barrier
	s_and_saveexec_b64 s[0:1], s[2:3]
	s_cbranch_execz .LBB0_807
	s_lshl_b32 s2, s8, 2
	v_mov_b32_e32 v177, 0
	s_ashr_i32 s3, s2, 31
	v_lshl_add_u64 v[0:1], s[4:5], 0, v[176:177]
	s_lshl_b64 s[4:5], s[2:3], 10
	v_lshl_add_u64 v[2:3], v[0:1], 0, s[4:5]
	s_or_b32 s4, s2, 1
	s_ashr_i32 s5, s4, 31
	s_lshl_b64 s[4:5], s[4:5], 10
	global_load_dword v4, v[2:3], off sc1
	v_lshl_add_u64 v[2:3], v[0:1], 0, s[4:5]
	s_or_b32 s4, s2, 2
	s_ashr_i32 s5, s4, 31
	s_or_b32 s2, s2, 3
	s_lshl_b64 s[4:5], s[4:5], 10
	s_ashr_i32 s3, s2, 31
	global_load_dword v5, v[2:3], off sc1
	v_lshl_add_u64 v[2:3], v[0:1], 0, s[4:5]
	s_lshl_b64 s[2:3], s[2:3], 10
	global_load_dword v2, v[2:3], off sc1
	v_lshl_add_u64 v[0:1], v[0:1], 0, s[2:3]
	global_load_dword v0, v[0:1], off sc1
	s_waitcnt vmcnt(3)
	v_add_f32_e32 v1, 0, v4
	s_waitcnt vmcnt(2)
	v_add_f32_e32 v1, v1, v5
	s_waitcnt vmcnt(1)
	v_add_f32_e32 v1, v1, v2
	s_waitcnt vmcnt(0)
	v_add_f32_e32 v0, v1, v0
	v_mov_b32_e32 v1, 0x358637bd
	v_fmac_f32_e32 v1, 0x3a800000, v0
	v_rsq_f32_e32 v0, v1
	v_add_u32_e32 v1, 0, v176
	ds_write_b32 v1, v0 offset:4096
